# exchange-barrier landed-DMA guarantee with the intended per-role counts (wave index read from its spill lane; s63 is a softmax constant in this phase)
# speedup vs baseline: 1.0089x; 1.0057x over previous
.LBB0_458:
	v_readlane_b32 s2, v255, 27
	v_readlane_b32 s21, v255, 10
	s_cmp_gt_u32 s21, 3
	s_cbranch_scc1 .Ldf_w_c1
	s_cmp_lg_u32 s95, 0
	s_cbranch_scc1 .Ldf_w_cl
	s_waitcnt vmcnt(16)
	s_branch .Ldf_w_done
